# v61 + grid barrier: waiting workgroups poll the cross-XCD release generation directly instead of the per-XCD word (one hop less on the release path)
# speedup vs baseline: 1.0099x; 1.0099x over previous
; __device__ __forceinline__ unsigned xb_ld(unsigned* p)              { return __hip_atomic_load(p, __ATOMIC_RELAXED, __HIP_MEMORY_SCOPE_AGENT); }
; __device__ __forceinline__ unsigned xb_add(unsigned* p, unsigned v) { return __hip_atomic_fetch_add(p, v, __ATOMIC_RELAXED, __HIP_MEMORY_SCOPE_AGENT); }
; #define XB_SPIN(cond, bar) do { unsigned _sp = 0; while (cond) { __builtin_amdgcn_s_sleep(1); \
;     if ((++_sp & 255u) == 0u) { if (xb_ld(&(bar)[XB_TMO])) break; if (_sp > XB_SPIN_CAP) { atomicAdd(&(bar)[XB_TMO], 1u); break; } } } } while (0)
; __device__ __forceinline__ void xcd_barrier(const XcdBarrier& b) {
;     ...
;         const unsigned old = xb_add(&bar[XB_XSUB(b.x)], 1u);
;         const unsigned gen = old / nloc;
;         if (old + 1u == (gen + 1u) * nloc) {
;             __builtin_amdgcn_fence(__ATOMIC_RELEASE, "agent");
;             asm volatile("s_waitcnt vmcnt(0)" ::: "memory");
;             const unsigned og = xb_add(&bar[XB_TOP], 1u);
;             const unsigned tg = og / nx;
;             if (og + 1u == (tg + 1u) * nx) xb_add(&bar[XB_TOPGEN], 1u);
;             else XB_SPIN(xb_ld(&bar[XB_TOPGEN]) == tg, bar);
;             __builtin_amdgcn_fence(__ATOMIC_ACQUIRE, "agent");
;             xb_add(&bar[XB_XGEN(b.x)], 1u);
;             asm volatile("s_waitcnt vmcnt(0)" ::: "memory");
;         } else {
;             XB_SPIN(xb_ld(&bar[XB_XGEN(b.x)]) == gen, bar);
.LBB0_216:
	s_lshl_b32 s74, s68, 6
	s_lshl_b64 s[4:5], s[74:75], 2
	s_add_u32 s8, s88, s4
	s_addc_u32 s9, s89, s5
	v_mov_b32_e32 v1, 0x1000
	global_atomic_add v4, v1, v252, s[8:9] offset:1024 sc0
	v_cvt_f32_u32_e32 v1, v3
	v_sub_u32_e32 v5, 0, v3
	v_rcp_iflag_f32_e32 v1, v1
	s_nop 0
	v_mul_f32_e32 v1, 0x4f7ffffe, v1
	v_cvt_u32_f32_e32 v1, v1
	v_mul_lo_u32 v5, v5, v1
	v_mul_hi_u32 v5, v1, v5
	v_add_u32_e32 v1, v1, v5
	s_waitcnt vmcnt(0)
	v_mul_hi_u32 v1, v4, v1
	v_mul_lo_u32 v5, v1, v3
	v_sub_u32_e32 v5, v4, v5
	v_add_u32_e32 v6, 1, v1
	v_cmp_ge_u32_e32 vcc, v5, v3
	v_add_u32_e32 v4, 1, v4
	s_nop 0
	v_cndmask_b32_e32 v1, v1, v6, vcc
	v_sub_u32_e32 v6, v5, v3
	v_cndmask_b32_e32 v5, v5, v6, vcc
	v_add_u32_e32 v6, 1, v1
	v_cmp_ge_u32_e32 vcc, v5, v3
	s_nop 1
	v_cndmask_b32_e32 v1, v1, v6, vcc
	v_mul_lo_u32 v5, v3, v1
	v_add_u32_e32 v3, v5, v3
	v_cmp_ne_u32_e32 vcc, v4, v3
	s_and_saveexec_b64 s[4:5], vcc
	s_xor_b64 s[10:11], exec, s[4:5]
	s_cbranch_execz .LBB0_229
	s_waitcnt lgkmcnt(0)
	global_load_dword v2, v253, s[8:9] offset:1024 sc1
	s_add_u32 s14, s88, 0x3500
	s_addc_u32 s15, s89, 0
	s_waitcnt vmcnt(0)
	v_cmp_eq_u32_e32 vcc, v2, v1
	s_and_saveexec_b64 s[12:13], vcc
	s_cbranch_execz .LBB0_228
	s_mov_b32 s4, 1
	s_mov_b64 s[16:17], 0
	s_branch .LBB0_220

; __device__ __forceinline__ unsigned xb_ld(unsigned* p)              { return __hip_atomic_load(p, __ATOMIC_RELAXED, __HIP_MEMORY_SCOPE_AGENT); }
; __device__ __forceinline__ unsigned xb_add(unsigned* p, unsigned v) { return __hip_atomic_fetch_add(p, v, __ATOMIC_RELAXED, __HIP_MEMORY_SCOPE_AGENT); }
; #define XB_SPIN(cond, bar) do { unsigned _sp = 0; while (cond) { __builtin_amdgcn_s_sleep(1); \
;     if ((++_sp & 255u) == 0u) { if (xb_ld(&(bar)[XB_TMO])) break; if (_sp > XB_SPIN_CAP) { atomicAdd(&(bar)[XB_TMO], 1u); break; } } } } while (0)
; __device__ __forceinline__ void xcd_barrier(const XcdBarrier& b) {
;     ...
;         const unsigned old = xb_add(&bar[XB_XSUB(b.x)], 1u);
;         const unsigned gen = old / nloc;
;         if (old + 1u == (gen + 1u) * nloc) {
;             __builtin_amdgcn_fence(__ATOMIC_RELEASE, "agent");
;             asm volatile("s_waitcnt vmcnt(0)" ::: "memory");
;             const unsigned og = xb_add(&bar[XB_TOP], 1u);
;             const unsigned tg = og / nx;
;             if (og + 1u == (tg + 1u) * nx) xb_add(&bar[XB_TOPGEN], 1u);
;             else XB_SPIN(xb_ld(&bar[XB_TOPGEN]) == tg, bar);
;             __builtin_amdgcn_fence(__ATOMIC_ACQUIRE, "agent");
;             xb_add(&bar[XB_XGEN(b.x)], 1u);
;             asm volatile("s_waitcnt vmcnt(0)" ::: "memory");
;         } else {
;             XB_SPIN(xb_ld(&bar[XB_XGEN(b.x)]) == gen, bar);
.LBB0_310:
	s_lshl_b32 s74, s90, 6
	s_lshl_b64 s[4:5], s[74:75], 2
	s_add_u32 s8, s88, s4
	s_addc_u32 s9, s89, s5
	v_mov_b32_e32 v1, 0x1000
	global_atomic_add v4, v1, v252, s[8:9] offset:1024 sc0
	v_cvt_f32_u32_e32 v1, v3
	v_sub_u32_e32 v5, 0, v3
	v_rcp_iflag_f32_e32 v1, v1
	s_nop 0
	v_mul_f32_e32 v1, 0x4f7ffffe, v1
	v_cvt_u32_f32_e32 v1, v1
	v_mul_lo_u32 v5, v5, v1
	v_mul_hi_u32 v5, v1, v5
	v_add_u32_e32 v1, v1, v5
	s_waitcnt vmcnt(0)
	v_mul_hi_u32 v1, v4, v1
	v_mul_lo_u32 v5, v1, v3
	v_sub_u32_e32 v5, v4, v5
	v_add_u32_e32 v6, 1, v1
	v_cmp_ge_u32_e32 vcc, v5, v3
	v_add_u32_e32 v4, 1, v4
	s_nop 0
	v_cndmask_b32_e32 v1, v1, v6, vcc
	v_sub_u32_e32 v6, v5, v3
	v_cndmask_b32_e32 v5, v5, v6, vcc
	v_add_u32_e32 v6, 1, v1
	v_cmp_ge_u32_e32 vcc, v5, v3
	s_nop 1
	v_cndmask_b32_e32 v1, v1, v6, vcc
	v_mul_lo_u32 v5, v3, v1
	v_add_u32_e32 v3, v5, v3
	v_cmp_ne_u32_e32 vcc, v4, v3
	s_and_saveexec_b64 s[4:5], vcc
	s_xor_b64 s[10:11], exec, s[4:5]
	s_cbranch_execz .LBB0_323
	s_waitcnt lgkmcnt(0)
	global_load_dword v2, v253, s[8:9] offset:1024 sc1
	s_add_u32 s14, s88, 0x3500
	s_addc_u32 s15, s89, 0
	s_waitcnt vmcnt(0)
	v_cmp_eq_u32_e32 vcc, v2, v1
	s_and_saveexec_b64 s[12:13], vcc
	s_cbranch_execz .LBB0_322
	s_mov_b32 s2, 1
	s_mov_b64 s[16:17], 0
	s_branch .LBB0_314

; __device__ __forceinline__ unsigned xb_ld(unsigned* p)              { return __hip_atomic_load(p, __ATOMIC_RELAXED, __HIP_MEMORY_SCOPE_AGENT); }
; __device__ __forceinline__ unsigned xb_add(unsigned* p, unsigned v) { return __hip_atomic_fetch_add(p, v, __ATOMIC_RELAXED, __HIP_MEMORY_SCOPE_AGENT); }
; #define XB_SPIN(cond, bar) do { unsigned _sp = 0; while (cond) { __builtin_amdgcn_s_sleep(1); \
;     if ((++_sp & 255u) == 0u) { if (xb_ld(&(bar)[XB_TMO])) break; if (_sp > XB_SPIN_CAP) { atomicAdd(&(bar)[XB_TMO], 1u); break; } } } } while (0)
; __device__ __forceinline__ void xcd_barrier(const XcdBarrier& b) {
;     ...
;         const unsigned old = xb_add(&bar[XB_XSUB(b.x)], 1u);
;         const unsigned gen = old / nloc;
;         if (old + 1u == (gen + 1u) * nloc) {
;             __builtin_amdgcn_fence(__ATOMIC_RELEASE, "agent");
;             asm volatile("s_waitcnt vmcnt(0)" ::: "memory");
;             const unsigned og = xb_add(&bar[XB_TOP], 1u);
;             const unsigned tg = og / nx;
;             if (og + 1u == (tg + 1u) * nx) xb_add(&bar[XB_TOPGEN], 1u);
;             else XB_SPIN(xb_ld(&bar[XB_TOPGEN]) == tg, bar);
;             __builtin_amdgcn_fence(__ATOMIC_ACQUIRE, "agent");
;             xb_add(&bar[XB_XGEN(b.x)], 1u);
;             asm volatile("s_waitcnt vmcnt(0)" ::: "memory");
;         } else {
;             XB_SPIN(xb_ld(&bar[XB_XGEN(b.x)]) == gen, bar);
.LBB0_573:
	s_lshl_b32 s74, s90, 6
	s_lshl_b64 s[4:5], s[74:75], 2
	s_add_u32 s6, s88, s4
	s_addc_u32 s7, s89, s5
	v_mov_b32_e32 v1, 0x1000
	global_atomic_add v4, v1, v252, s[6:7] offset:1024 sc0
	v_cvt_f32_u32_e32 v1, v3
	v_sub_u32_e32 v5, 0, v3
	v_rcp_iflag_f32_e32 v1, v1
	s_nop 0
	v_mul_f32_e32 v1, 0x4f7ffffe, v1
	v_cvt_u32_f32_e32 v1, v1
	v_mul_lo_u32 v5, v5, v1
	v_mul_hi_u32 v5, v1, v5
	v_add_u32_e32 v1, v1, v5
	s_waitcnt vmcnt(0)
	v_mul_hi_u32 v1, v4, v1
	v_mul_lo_u32 v5, v1, v3
	v_sub_u32_e32 v5, v4, v5
	v_add_u32_e32 v6, 1, v1
	v_cmp_ge_u32_e32 vcc, v5, v3
	v_add_u32_e32 v4, 1, v4
	s_nop 0
	v_cndmask_b32_e32 v1, v1, v6, vcc
	v_sub_u32_e32 v6, v5, v3
	v_cndmask_b32_e32 v5, v5, v6, vcc
	v_add_u32_e32 v6, 1, v1
	v_cmp_ge_u32_e32 vcc, v5, v3
	s_nop 1
	v_cndmask_b32_e32 v1, v1, v6, vcc
	v_mul_lo_u32 v5, v3, v1
	v_add_u32_e32 v3, v5, v3
	v_cmp_ne_u32_e32 vcc, v4, v3
	s_and_saveexec_b64 s[4:5], vcc
	s_xor_b64 s[8:9], exec, s[4:5]
	s_cbranch_execz .LBB0_586
	s_waitcnt lgkmcnt(0)
	global_load_dword v2, v253, s[6:7] offset:1024 sc1
	s_add_u32 s12, s88, 0x3500
	s_addc_u32 s13, s89, 0
	s_waitcnt vmcnt(0)
	v_cmp_eq_u32_e32 vcc, v2, v1
	s_and_saveexec_b64 s[10:11], vcc
	s_cbranch_execz .LBB0_585
	s_mov_b32 s4, 1
	s_mov_b64 s[14:15], 0
	s_branch .LBB0_577

; __device__ __forceinline__ unsigned xb_ld(unsigned* p)              { return __hip_atomic_load(p, __ATOMIC_RELAXED, __HIP_MEMORY_SCOPE_AGENT); }
; __device__ __forceinline__ unsigned xb_add(unsigned* p, unsigned v) { return __hip_atomic_fetch_add(p, v, __ATOMIC_RELAXED, __HIP_MEMORY_SCOPE_AGENT); }
; #define XB_SPIN(cond, bar) do { unsigned _sp = 0; while (cond) { __builtin_amdgcn_s_sleep(1); \
;     if ((++_sp & 255u) == 0u) { if (xb_ld(&(bar)[XB_TMO])) break; if (_sp > XB_SPIN_CAP) { atomicAdd(&(bar)[XB_TMO], 1u); break; } } } } while (0)
; __device__ __forceinline__ void xcd_barrier(const XcdBarrier& b) {
;     ...
;         const unsigned old = xb_add(&bar[XB_XSUB(b.x)], 1u);
;         const unsigned gen = old / nloc;
;         if (old + 1u == (gen + 1u) * nloc) {
;             __builtin_amdgcn_fence(__ATOMIC_RELEASE, "agent");
;             asm volatile("s_waitcnt vmcnt(0)" ::: "memory");
;             const unsigned og = xb_add(&bar[XB_TOP], 1u);
;             const unsigned tg = og / nx;
;             if (og + 1u == (tg + 1u) * nx) xb_add(&bar[XB_TOPGEN], 1u);
;             else XB_SPIN(xb_ld(&bar[XB_TOPGEN]) == tg, bar);
;             __builtin_amdgcn_fence(__ATOMIC_ACQUIRE, "agent");
;             xb_add(&bar[XB_XGEN(b.x)], 1u);
;             asm volatile("s_waitcnt vmcnt(0)" ::: "memory");
;         } else {
;             XB_SPIN(xb_ld(&bar[XB_XGEN(b.x)]) == gen, bar);
.LBB0_1015:
	s_lshl_b32 s74, s68, 6
	s_lshl_b64 s[4:5], s[74:75], 2
	s_add_u32 s8, s88, s4
	s_addc_u32 s9, s89, s5
	v_mov_b32_e32 v1, 0x1000
	global_atomic_add v4, v1, v252, s[8:9] offset:1024 sc0
	v_cvt_f32_u32_e32 v1, v3
	v_sub_u32_e32 v5, 0, v3
	v_rcp_iflag_f32_e32 v1, v1
	s_nop 0
	v_mul_f32_e32 v1, 0x4f7ffffe, v1
	v_cvt_u32_f32_e32 v1, v1
	v_mul_lo_u32 v5, v5, v1
	v_mul_hi_u32 v5, v1, v5
	v_add_u32_e32 v1, v1, v5
	s_waitcnt vmcnt(0)
	v_mul_hi_u32 v1, v4, v1
	v_mul_lo_u32 v5, v1, v3
	v_sub_u32_e32 v5, v4, v5
	v_add_u32_e32 v6, 1, v1
	v_cmp_ge_u32_e32 vcc, v5, v3
	v_add_u32_e32 v4, 1, v4
	s_nop 0
	v_cndmask_b32_e32 v1, v1, v6, vcc
	v_sub_u32_e32 v6, v5, v3
	v_cndmask_b32_e32 v5, v5, v6, vcc
	v_add_u32_e32 v6, 1, v1
	v_cmp_ge_u32_e32 vcc, v5, v3
	s_nop 1
	v_cndmask_b32_e32 v1, v1, v6, vcc
	v_mul_lo_u32 v5, v3, v1
	v_add_u32_e32 v3, v5, v3
	v_cmp_ne_u32_e32 vcc, v4, v3
	s_and_saveexec_b64 s[4:5], vcc
	s_xor_b64 s[10:11], exec, s[4:5]
	s_cbranch_execz .LBB0_1028
	s_waitcnt lgkmcnt(0)
	global_load_dword v2, v253, s[8:9] offset:1024 sc1
	s_add_u32 s14, s88, 0x3500
	s_addc_u32 s15, s89, 0
	s_waitcnt vmcnt(0)
	v_cmp_eq_u32_e32 vcc, v2, v1
	s_and_saveexec_b64 s[12:13], vcc
	s_cbranch_execz .LBB0_1027
	s_mov_b32 s2, 1
	s_mov_b64 s[16:17], 0
	s_branch .LBB0_1019

; __device__ __forceinline__ unsigned xb_ld(unsigned* p)              { return __hip_atomic_load(p, __ATOMIC_RELAXED, __HIP_MEMORY_SCOPE_AGENT); }
; __device__ __forceinline__ unsigned xb_add(unsigned* p, unsigned v) { return __hip_atomic_fetch_add(p, v, __ATOMIC_RELAXED, __HIP_MEMORY_SCOPE_AGENT); }
; #define XB_SPIN(cond, bar) do { unsigned _sp = 0; while (cond) { __builtin_amdgcn_s_sleep(1); \
;     if ((++_sp & 255u) == 0u) { if (xb_ld(&(bar)[XB_TMO])) break; if (_sp > XB_SPIN_CAP) { atomicAdd(&(bar)[XB_TMO], 1u); break; } } } } while (0)
; __device__ __forceinline__ void xcd_barrier(const XcdBarrier& b) {
;     ...
;         const unsigned old = xb_add(&bar[XB_XSUB(b.x)], 1u);
;         const unsigned gen = old / nloc;
;         if (old + 1u == (gen + 1u) * nloc) {
;             __builtin_amdgcn_fence(__ATOMIC_RELEASE, "agent");
;             asm volatile("s_waitcnt vmcnt(0)" ::: "memory");
;             const unsigned og = xb_add(&bar[XB_TOP], 1u);
;             const unsigned tg = og / nx;
;             if (og + 1u == (tg + 1u) * nx) xb_add(&bar[XB_TOPGEN], 1u);
;             else XB_SPIN(xb_ld(&bar[XB_TOPGEN]) == tg, bar);
;             __builtin_amdgcn_fence(__ATOMIC_ACQUIRE, "agent");
;             xb_add(&bar[XB_XGEN(b.x)], 1u);
;             asm volatile("s_waitcnt vmcnt(0)" ::: "memory");
;         } else {
;             XB_SPIN(xb_ld(&bar[XB_XGEN(b.x)]) == gen, bar);
.LBB0_1278:
	s_lshl_b32 s74, s90, 6
	s_lshl_b64 s[6:7], s[74:75], 2
	s_add_u32 s6, s88, s6
	s_addc_u32 s7, s89, s7
	v_mov_b32_e32 v1, 0x1000
	global_atomic_add v4, v1, v252, s[6:7] offset:1024 sc0
	v_cvt_f32_u32_e32 v1, v3
	v_sub_u32_e32 v5, 0, v3
	v_rcp_iflag_f32_e32 v1, v1
	s_nop 0
	v_mul_f32_e32 v1, 0x4f7ffffe, v1
	v_cvt_u32_f32_e32 v1, v1
	v_mul_lo_u32 v5, v5, v1
	v_mul_hi_u32 v5, v1, v5
	v_add_u32_e32 v1, v1, v5
	s_waitcnt vmcnt(0)
	v_mul_hi_u32 v1, v4, v1
	v_mul_lo_u32 v5, v1, v3
	v_sub_u32_e32 v5, v4, v5
	v_add_u32_e32 v6, 1, v1
	v_cmp_ge_u32_e32 vcc, v5, v3
	v_add_u32_e32 v4, 1, v4
	s_nop 0
	v_cndmask_b32_e32 v1, v1, v6, vcc
	v_sub_u32_e32 v6, v5, v3
	v_cndmask_b32_e32 v5, v5, v6, vcc
	v_add_u32_e32 v6, 1, v1
	v_cmp_ge_u32_e32 vcc, v5, v3
	s_nop 1
	v_cndmask_b32_e32 v1, v1, v6, vcc
	v_mul_lo_u32 v5, v3, v1
	v_add_u32_e32 v3, v5, v3
	v_cmp_ne_u32_e32 vcc, v4, v3
	s_and_saveexec_b64 s[8:9], vcc
	s_xor_b64 s[8:9], exec, s[8:9]
	s_cbranch_execz .LBB0_1291
	s_waitcnt lgkmcnt(0)
	global_load_dword v2, v253, s[6:7] offset:1024 sc1
	s_add_u32 s12, s88, 0x3500
	s_addc_u32 s13, s89, 0
	s_waitcnt vmcnt(0)
	v_cmp_eq_u32_e32 vcc, v2, v1
	s_and_saveexec_b64 s[10:11], vcc
	s_cbranch_execz .LBB0_1290
	s_mov_b32 s24, 1
	s_mov_b64 s[14:15], 0
	s_branch .LBB0_1282

; __device__ __forceinline__ unsigned xb_ld(unsigned* p)              { return __hip_atomic_load(p, __ATOMIC_RELAXED, __HIP_MEMORY_SCOPE_AGENT); }
; __device__ __forceinline__ unsigned xb_add(unsigned* p, unsigned v) { return __hip_atomic_fetch_add(p, v, __ATOMIC_RELAXED, __HIP_MEMORY_SCOPE_AGENT); }
; #define XB_SPIN(cond, bar) do { unsigned _sp = 0; while (cond) { __builtin_amdgcn_s_sleep(1); \
;     if ((++_sp & 255u) == 0u) { if (xb_ld(&(bar)[XB_TMO])) break; if (_sp > XB_SPIN_CAP) { atomicAdd(&(bar)[XB_TMO], 1u); break; } } } } while (0)
; __device__ __forceinline__ void xcd_barrier(const XcdBarrier& b) {
;     ...
;         const unsigned old = xb_add(&bar[XB_XSUB(b.x)], 1u);
;         const unsigned gen = old / nloc;
;         if (old + 1u == (gen + 1u) * nloc) {
;             __builtin_amdgcn_fence(__ATOMIC_RELEASE, "agent");
;             asm volatile("s_waitcnt vmcnt(0)" ::: "memory");
;             const unsigned og = xb_add(&bar[XB_TOP], 1u);
;             const unsigned tg = og / nx;
;             if (og + 1u == (tg + 1u) * nx) xb_add(&bar[XB_TOPGEN], 1u);
;             else XB_SPIN(xb_ld(&bar[XB_TOPGEN]) == tg, bar);
;             __builtin_amdgcn_fence(__ATOMIC_ACQUIRE, "agent");
;             xb_add(&bar[XB_XGEN(b.x)], 1u);
;             asm volatile("s_waitcnt vmcnt(0)" ::: "memory");
;         } else {
;             XB_SPIN(xb_ld(&bar[XB_XGEN(b.x)]) == gen, bar);
.LBB0_1402:
	s_lshl_b32 s74, s90, 6
	s_lshl_b64 s[6:7], s[74:75], 2
	s_add_u32 s6, s88, s6
	s_addc_u32 s7, s89, s7
	v_mov_b32_e32 v1, 0x1000
	global_atomic_add v4, v1, v252, s[6:7] offset:1024 sc0
	v_cvt_f32_u32_e32 v1, v3
	v_sub_u32_e32 v5, 0, v3
	v_rcp_iflag_f32_e32 v1, v1
	s_nop 0
	v_mul_f32_e32 v1, 0x4f7ffffe, v1
	v_cvt_u32_f32_e32 v1, v1
	v_mul_lo_u32 v5, v5, v1
	v_mul_hi_u32 v5, v1, v5
	v_add_u32_e32 v1, v1, v5
	s_waitcnt vmcnt(0)
	v_mul_hi_u32 v1, v4, v1
	v_mul_lo_u32 v5, v1, v3
	v_sub_u32_e32 v5, v4, v5
	v_add_u32_e32 v6, 1, v1
	v_cmp_ge_u32_e32 vcc, v5, v3
	v_add_u32_e32 v4, 1, v4
	s_nop 0
	v_cndmask_b32_e32 v1, v1, v6, vcc
	v_sub_u32_e32 v6, v5, v3
	v_cndmask_b32_e32 v5, v5, v6, vcc
	v_add_u32_e32 v6, 1, v1
	v_cmp_ge_u32_e32 vcc, v5, v3
	s_nop 1
	v_cndmask_b32_e32 v1, v1, v6, vcc
	v_mul_lo_u32 v5, v3, v1
	v_add_u32_e32 v3, v5, v3
	v_cmp_ne_u32_e32 vcc, v4, v3
	s_and_saveexec_b64 s[8:9], vcc
	s_xor_b64 s[8:9], exec, s[8:9]
	s_cbranch_execz .LBB0_1415
	s_waitcnt lgkmcnt(0)
	global_load_dword v2, v253, s[6:7] offset:1024 sc1
	s_add_u32 s12, s88, 0x3500
	s_addc_u32 s13, s89, 0
	s_waitcnt vmcnt(0)
	v_cmp_eq_u32_e32 vcc, v2, v1
	s_and_saveexec_b64 s[10:11], vcc
	s_cbranch_execz .LBB0_1414
	s_mov_b32 s2, 1
	s_mov_b64 s[14:15], 0
	s_branch .LBB0_1406

; __device__ __forceinline__ unsigned xb_ld(unsigned* p)              { return __hip_atomic_load(p, __ATOMIC_RELAXED, __HIP_MEMORY_SCOPE_AGENT); }
; __device__ __forceinline__ unsigned xb_add(unsigned* p, unsigned v) { return __hip_atomic_fetch_add(p, v, __ATOMIC_RELAXED, __HIP_MEMORY_SCOPE_AGENT); }
; #define XB_SPIN(cond, bar) do { unsigned _sp = 0; while (cond) { __builtin_amdgcn_s_sleep(1); \
;     if ((++_sp & 255u) == 0u) { if (xb_ld(&(bar)[XB_TMO])) break; if (_sp > XB_SPIN_CAP) { atomicAdd(&(bar)[XB_TMO], 1u); break; } } } } while (0)
; __device__ __forceinline__ void xcd_barrier(const XcdBarrier& b) {
;     ...
;         const unsigned old = xb_add(&bar[XB_XSUB(b.x)], 1u);
;         const unsigned gen = old / nloc;
;         if (old + 1u == (gen + 1u) * nloc) {
;             __builtin_amdgcn_fence(__ATOMIC_RELEASE, "agent");
;             asm volatile("s_waitcnt vmcnt(0)" ::: "memory");
;             const unsigned og = xb_add(&bar[XB_TOP], 1u);
;             const unsigned tg = og / nx;
;             if (og + 1u == (tg + 1u) * nx) xb_add(&bar[XB_TOPGEN], 1u);
;             else XB_SPIN(xb_ld(&bar[XB_TOPGEN]) == tg, bar);
;             __builtin_amdgcn_fence(__ATOMIC_ACQUIRE, "agent");
;             xb_add(&bar[XB_XGEN(b.x)], 1u);
;             asm volatile("s_waitcnt vmcnt(0)" ::: "memory");
;         } else {
;             XB_SPIN(xb_ld(&bar[XB_XGEN(b.x)]) == gen, bar);
.LBB0_1472:
	s_lshl_b32 s2, s68, 6
	s_mov_b32 s3, 0
	s_lshl_b64 s[2:3], s[2:3], 2
	s_add_u32 s2, s88, s2
	s_addc_u32 s3, s89, s3
	v_mov_b32_e32 v1, 0x1000
	v_mov_b32_e32 v3, 1
	global_atomic_add v3, v1, v3, s[2:3] offset:1024 sc0
	v_cvt_f32_u32_e32 v1, v2
	v_sub_u32_e32 v4, 0, v2
	v_rcp_iflag_f32_e32 v1, v1
	s_nop 0
	v_mul_f32_e32 v1, 0x4f7ffffe, v1
	v_cvt_u32_f32_e32 v1, v1
	v_mul_lo_u32 v4, v4, v1
	v_mul_hi_u32 v4, v1, v4
	v_add_u32_e32 v1, v1, v4
	s_waitcnt vmcnt(0)
	v_mul_hi_u32 v1, v3, v1
	v_mul_lo_u32 v4, v1, v2
	v_sub_u32_e32 v4, v3, v4
	v_add_u32_e32 v5, 1, v1
	v_cmp_ge_u32_e32 vcc, v4, v2
	v_add_u32_e32 v3, 1, v3
	s_nop 0
	v_cndmask_b32_e32 v1, v1, v5, vcc
	v_sub_u32_e32 v5, v4, v2
	v_cndmask_b32_e32 v4, v4, v5, vcc
	v_add_u32_e32 v5, 1, v1
	v_cmp_ge_u32_e32 vcc, v4, v2
	s_nop 1
	v_cndmask_b32_e32 v1, v1, v5, vcc
	v_mul_lo_u32 v4, v2, v1
	v_add_u32_e32 v2, v4, v2
	v_cmp_ne_u32_e32 vcc, v3, v2
	s_and_saveexec_b64 s[4:5], vcc
	s_xor_b64 s[6:7], exec, s[4:5]
	s_cbranch_execz .LBB0_1485
	s_waitcnt lgkmcnt(0)
	v_mov_b32_e32 v0, 0x2000
	global_load_dword v0, v0, s[2:3] offset:1024 sc1
	s_add_u32 s12, s88, 0x3500
	s_addc_u32 s13, s89, 0
	s_waitcnt vmcnt(0)
	v_cmp_eq_u32_e32 vcc, v0, v1
	s_and_saveexec_b64 s[8:9], vcc
	s_cbranch_execz .LBB0_1484
	s_mov_b32 s4, 1
	s_mov_b64 s[14:15], 0
	v_mov_b32_e32 v0, 0
	s_branch .LBB0_1476
